# counted wait refinement: vmcnt(5) (exact) instead of vmcnt(4) at the top of the two specialised row-pass loops
# speedup vs baseline: 1.0054x; 1.0054x over previous
.LBB0_403:
	s_add_i32 s14, s8, 0xffff8000
	s_and_b64 s[4:5], s[4:5], exec
	s_cselect_b32 s5, s9, 0
	s_cselect_b32 s4, s8, s14
	s_cselect_b32 s14, s75, s10
	s_cselect_b32 s15, s74, s2
	s_lshl_b64 s[4:5], s[4:5], 12
	s_add_u32 s4, s15, s4
	s_addc_u32 s5, s14, s5
	s_waitcnt vmcnt(5)
	v_mov_b32_e32 v80, v106
	v_mov_b32_e32 v81, v107
	v_mov_b32_e32 v82, v108
	v_mov_b32_e32 v83, v109
	v_mov_b32_e32 v76, v110
	v_mov_b32_e32 v77, v111
	v_mov_b32_e32 v78, v112
	v_mov_b32_e32 v79, v113
	v_mov_b32_e32 v72, v114
	v_mov_b32_e32 v73, v115
	v_mov_b32_e32 v74, v116
	v_mov_b32_e32 v75, v117
	v_mov_b32_e32 v68, v118
	v_mov_b32_e32 v69, v119
	v_mov_b32_e32 v70, v120
	v_mov_b32_e32 v71, v121
	s_add_i32 s100, s8, s34
	s_cmp_ge_i32 s100, 0x8200
	s_cbranch_scc1 .Lrpf_skip_f0
	s_add_i32 s101, s100, 0xffff8000
	s_cmp_lt_i32 s100, 0x8000
	s_cselect_b32 s100, s100, s101
	s_cselect_b32 s15, s74, s2
	s_cselect_b32 s14, s75, s10
	s_mov_b32 s101, 0
	s_lshl_b64 s[100:101], s[100:101], 12
	s_add_u32 s100, s15, s100
	s_addc_u32 s101, s14, s101
	global_load_dwordx4 v[106:109], v96, s[100:101]
	global_load_dwordx4 v[110:113], v96, s[100:101] offset:1024
	global_load_dwordx4 v[114:117], v96, s[100:101] offset:2048
	global_load_dwordx4 v[118:121], v96, s[100:101] offset:3072

.LBB0_853:
	s_add_i32 s14, s8, 0xffff8000
	s_and_b64 s[4:5], s[4:5], exec
	s_cselect_b32 s5, s9, 0
	s_cselect_b32 s4, s8, s14
	s_cselect_b32 s14, s75, s10
	s_cselect_b32 s15, s74, s2
	s_lshl_b64 s[4:5], s[4:5], 12
	s_add_u32 s4, s15, s4
	s_addc_u32 s5, s14, s5
	s_waitcnt vmcnt(5)
	v_mov_b32_e32 v80, v106
	v_mov_b32_e32 v81, v107
	v_mov_b32_e32 v82, v108
	v_mov_b32_e32 v83, v109
	v_mov_b32_e32 v76, v110
	v_mov_b32_e32 v77, v111
	v_mov_b32_e32 v78, v112
	v_mov_b32_e32 v79, v113
	v_mov_b32_e32 v72, v114
	v_mov_b32_e32 v73, v115
	v_mov_b32_e32 v74, v116
	v_mov_b32_e32 v75, v117
	v_mov_b32_e32 v68, v118
	v_mov_b32_e32 v69, v119
	v_mov_b32_e32 v70, v120
	v_mov_b32_e32 v71, v121
	s_add_i32 s100, s8, s34
	s_cmp_ge_i32 s100, s40
	s_cbranch_scc1 .Lrpf_skip_wo
	s_add_i32 s101, s100, 0xffff8000
	s_cmp_lt_i32 s100, 0x8000
	s_cselect_b32 s100, s100, s101
	s_cselect_b32 s15, s74, s2
	s_cselect_b32 s14, s75, s10
	s_mov_b32 s101, 0
	s_lshl_b64 s[100:101], s[100:101], 12
	s_add_u32 s100, s15, s100
	s_addc_u32 s101, s14, s101
	global_load_dwordx4 v[106:109], v96, s[100:101]
	global_load_dwordx4 v[110:113], v96, s[100:101] offset:1024
	global_load_dwordx4 v[114:117], v96, s[100:101] offset:2048
	global_load_dwordx4 v[118:121], v96, s[100:101] offset:3072
